# GEMM K-loop: k=0 and k=1 MFMAs of each accumulator issued back to back (accumulate chain via SrcC forwarding, tiles in snake order) on top of the hand-off trim and ph0 changes
# speedup vs baseline: 1.0176x; 1.0176x over previous
; #define PG8_STAGE(bufoff, gbase, voff) do { _Pragma("unroll") for (int _i = 0; _i < 2; ++_i) \
;         __builtin_amdgcn_global_load_lds((const unsigned*)((const char*)(gbase) + (voff)[_i]), (PG8_LAS unsigned*)(lds + (bufoff) + ldsw + _i * 8192), 16, 0, 0); } while (0)
; #define PG8_LDA(dst, b, h) do { _Pragma("unroll") for (int m = 0; m < 4; ++m) _Pragma("unroll") for (int k = 0; k < 2; ++k) dst[m][k] = *(const PG8_LAS bf16x8*)(lds + PG8_SA(b, h) + aoff + m * 2048 + k * 1024); } while (0)
; #define PG8_LDB(dst, b, h) do { _Pragma("unroll") for (int n = 0; n < 2; ++n) _Pragma("unroll") for (int k = 0; k < 2; ++k) dst[n][k] = *(const PG8_LAS bf16x8*)(lds + PG8_SB(b, h) + boff + n * 2048 + k * 1024); } while (0)
; #define PG8_MMA(ai, bj, At, Bt) do { __builtin_amdgcn_s_setprio(1); _Pragma("unroll") for (int m = 0; m < 4; ++m) _Pragma("unroll") for (int n = 0; n < 2; ++n) _Pragma("unroll") for (int k = 0; k < 2; ++k) \
;         acc[ai][bj][m][n] = __builtin_amdgcn_mfma_f32_16x16x32_bf16(Bt[n][k], At[m][k], acc[ai][bj][m][n], 0, 0, 0); __builtin_amdgcn_s_setprio(0); } while (0)
; #define PG8_WAIT_V(n) asm volatile("s_waitcnt vmcnt(" #n ")" ::: "memory")
; template <class Epi, class Sched, bool ALIGN_EPI = false, bool SP2 = false>
; __device__ __forceinline__ void gemm_phase(PG8_LAS unsigned char* lds, const Gemm g, const Sched& S, const Epi& E) {
;     ...
;             PG8_LDB(B0, 0, 0); PG8_LDB(B1, 0, 1); PG8_SCHED; PG8_LDA(At, 0, 0); PG8_STAGE(PG8_SA(1, 1), a1 + hstep, voffA);
;             PG8_WAIT_V(8); PG8_WAIT_L(0); PG8_BAR; PG8_MMA(0, 0, At, B0); PG8_MMA(0, 1, At, B1); PG8_BAR; PG8_SCHED;
;             PG8_LDA(At, 0, 1); PG8_STAGE(PG8_SB(0, 0), b2, voffB); PG8_STAGE(PG8_SB(0, 1), b2 + hstep, voffB); PG8_STAGE(PG8_SA(0, 0), a2, voffA);
;             PG8_WAIT_V(8); PG8_WAIT_L(0); PG8_BAR; PG8_MMA(1, 0, At, B0); PG8_MMA(1, 1, At, B1); PG8_BAR; PG8_SCHED;
;             PG8_LDB(B0, 1, 0); PG8_LDB(B1, 1, 1); PG8_SCHED; PG8_LDA(At, 1, 0); PG8_STAGE(PG8_SA(0, 1), a2 + hstep, voffA);
;             PG8_WAIT_V(8); PG8_WAIT_L(0); PG8_BAR; PG8_MMA(0, 0, At, B0); PG8_MMA(0, 1, At, B1); PG8_BAR; PG8_SCHED;
;             PG8_LDA(At, 1, 1); PG8_STAGE(PG8_SB(1, 0), b3, voffB); PG8_STAGE(PG8_SB(1, 1), b3 + hstep, voffB); PG8_STAGE(PG8_SA(1, 0), a3, voffA);
;             PG8_WAIT_V(8); PG8_WAIT_L(0); PG8_BAR; PG8_MMA(1, 0, At, B0); PG8_MMA(1, 1, At, B1); PG8_BAR; PG8_SCHED;
.LBB0_56:
	s_add_i32 s2, s34, 2
	s_add_u32 s35, s28, s30
	s_addc_u32 s62, s29, s31
	s_add_u32 s63, s35, 0x100
	s_addc_u32 s35, s62, 0
	s_add_u32 s62, s60, s30
	s_addc_u32 s64, s61, s31
	s_add_i32 s65, 0, 0x10000
	s_cmp_eq_u32 s48, s34
	s_cselect_b32 s35, s1, s35
	s_cselect_b32 s34, s0, s63
	v_add_u32_e32 v0, s65, v188
	s_cselect_b32 s63, s27, s64
	s_cselect_b32 s62, s26, s62
	s_add_i32 s64, 0, 0x14000
	ds_read_b128 v[132:135], v0
	ds_read_b128 v[136:139], v0 offset:1024
	ds_read_b128 v[140:143], v0 offset:2048
	ds_read_b128 v[144:147], v0 offset:3072
	v_add_u32_e32 v0, s64, v188
	ds_read_b128 v[148:151], v0
	ds_read_b128 v[152:155], v0 offset:1024
	ds_read_b128 v[156:159], v0 offset:2048
	ds_read_b128 v[160:163], v0 offset:3072
	v_lshl_add_u64 v[2:3], v[204:205], 0, s[30:31]
	s_add_i32 m0, s43, 0xc000
	ds_read_b128 v[164:167], v235
	ds_read_b128 v[168:171], v235 offset:1024
	ds_read_b128 v[172:175], v235 offset:2048
	ds_read_b128 v[176:179], v235 offset:3072
	ds_read_b128 v[180:183], v235 offset:4096
	ds_read_b128 v[184:187], v235 offset:5120
	ds_read_b128 v[236:239], v235 offset:6144
	ds_read_b128 v[240:243], v235 offset:7168
	global_load_lds_dwordx4 v[2:3], off
	v_lshl_add_u64 v[2:3], v[206:207], 0, s[30:31]
	s_add_i32 m0, s43, 0xe000
	s_nop 0
	global_load_lds_dwordx4 v[2:3], off
	s_waitcnt vmcnt(8)
	s_waitcnt lgkmcnt(0)
	s_setprio 1
	s_barrier
	v_mfma_f32_16x16x32_bf16 v[116:119], v[132:135], v[164:167], v[116:119]
	v_mfma_f32_16x16x32_bf16 v[116:119], v[136:139], v[168:171], v[116:119]
	v_mfma_f32_16x16x32_bf16 v[120:123], v[140:143], v[164:167], v[120:123]
	v_mfma_f32_16x16x32_bf16 v[120:123], v[144:147], v[168:171], v[120:123]
	v_mfma_f32_16x16x32_bf16 v[104:107], v[140:143], v[172:175], v[104:107]
	v_mfma_f32_16x16x32_bf16 v[104:107], v[144:147], v[176:179], v[104:107]
	v_mfma_f32_16x16x32_bf16 v[100:103], v[132:135], v[172:175], v[100:103]
	v_mfma_f32_16x16x32_bf16 v[100:103], v[136:139], v[176:179], v[100:103]
	v_mfma_f32_16x16x32_bf16 v[76:79], v[132:135], v[180:183], v[76:79]
	v_mfma_f32_16x16x32_bf16 v[76:79], v[136:139], v[184:187], v[76:79]
	v_mfma_f32_16x16x32_bf16 v[80:83], v[140:143], v[180:183], v[80:83]
	v_mfma_f32_16x16x32_bf16 v[80:83], v[144:147], v[184:187], v[80:83]
	v_mfma_f32_16x16x32_bf16 v[48:51], v[140:143], v[236:239], v[48:51]
	v_mfma_f32_16x16x32_bf16 v[48:51], v[144:147], v[240:243], v[48:51]
	v_mfma_f32_16x16x32_bf16 v[44:47], v[132:135], v[236:239], v[44:47]
	v_mfma_f32_16x16x32_bf16 v[44:47], v[136:139], v[240:243], v[44:47]
	v_mfma_f32_16x16x32_bf16 v[124:127], v[148:151], v[164:167], v[124:127]
	v_mfma_f32_16x16x32_bf16 v[124:127], v[152:155], v[168:171], v[124:127]
	v_mfma_f32_16x16x32_bf16 v[128:131], v[156:159], v[164:167], v[128:131]
	v_mfma_f32_16x16x32_bf16 v[128:131], v[160:163], v[168:171], v[128:131]
	v_mfma_f32_16x16x32_bf16 v[112:115], v[156:159], v[172:175], v[112:115]
	v_mfma_f32_16x16x32_bf16 v[112:115], v[160:163], v[176:179], v[112:115]
	v_mfma_f32_16x16x32_bf16 v[108:111], v[148:151], v[172:175], v[108:111]
	v_mfma_f32_16x16x32_bf16 v[108:111], v[152:155], v[176:179], v[108:111]
	v_mfma_f32_16x16x32_bf16 v[92:95], v[148:151], v[180:183], v[92:95]
	v_mfma_f32_16x16x32_bf16 v[92:95], v[152:155], v[184:187], v[92:95]
	v_mfma_f32_16x16x32_bf16 v[96:99], v[156:159], v[180:183], v[96:99]
	v_mfma_f32_16x16x32_bf16 v[96:99], v[160:163], v[184:187], v[96:99]
	v_mfma_f32_16x16x32_bf16 v[72:75], v[156:159], v[236:239], v[72:75]
	v_mfma_f32_16x16x32_bf16 v[72:75], v[160:163], v[240:243], v[72:75]
	v_mfma_f32_16x16x32_bf16 v[68:71], v[148:151], v[236:239], v[68:71]
	v_mfma_f32_16x16x32_bf16 v[68:71], v[152:155], v[240:243], v[68:71]
	s_barrier
	s_setprio 0
	s_add_i32 s65, s65, s41
	v_lshl_add_u64 v[208:209], s[62:63], 0, v[192:193]
	s_mov_b32 m0, s65
	ds_read_b128 v[164:167], v235 offset:16384
	ds_read_b128 v[168:171], v235 offset:17408
	ds_read_b128 v[172:175], v235 offset:18432
	ds_read_b128 v[176:179], v235 offset:19456
	ds_read_b128 v[180:183], v235 offset:20480
	ds_read_b128 v[184:187], v235 offset:21504
	ds_read_b128 v[236:239], v235 offset:22528
	ds_read_b128 v[240:243], v235 offset:23552
	global_load_lds_dwordx4 v[208:209], off
	s_add_i32 m0, s65, 0x2000
	v_lshl_add_u64 v[244:245], s[62:63], 0, v[196:197]
	s_add_u32 s62, s62, s16
	s_addc_u32 s63, s63, 0
	s_add_i32 s64, s64, s41
	global_load_lds_dwordx4 v[244:245], off
	v_lshl_add_u64 v[246:247], s[62:63], 0, v[192:193]
	s_mov_b32 m0, s64
	v_lshl_add_u64 v[248:249], s[62:63], 0, v[196:197]
	global_load_lds_dwordx4 v[246:247], off
	s_add_i32 m0, s64, 0x2000
	v_lshl_add_u64 v[250:251], s[34:35], 0, v[190:191]
	global_load_lds_dwordx4 v[248:249], off
	s_mov_b32 m0, s43
	v_lshl_add_u64 v[212:213], s[34:35], 0, v[194:195]
	global_load_lds_dwordx4 v[250:251], off
	s_mov_b32 m0, s44
	s_nop 0
	global_load_lds_dwordx4 v[212:213], off
	s_waitcnt vmcnt(8)
	s_waitcnt lgkmcnt(0)
	s_setprio 1
	s_barrier
; #define PG8_STAGE(bufoff, gbase, voff) do { _Pragma("unroll") for (int _i = 0; _i < 2; ++_i) \
;         __builtin_amdgcn_global_load_lds((const unsigned*)((const char*)(gbase) + (voff)[_i]), (PG8_LAS unsigned*)(lds + (bufoff) + ldsw + _i * 8192), 16, 0, 0); } while (0)
; #define PG8_LDA(dst, b, h) do { _Pragma("unroll") for (int m = 0; m < 4; ++m) _Pragma("unroll") for (int k = 0; k < 2; ++k) dst[m][k] = *(const PG8_LAS bf16x8*)(lds + PG8_SA(b, h) + aoff + m * 2048 + k * 1024); } while (0)
; #define PG8_LDB(dst, b, h) do { _Pragma("unroll") for (int n = 0; n < 2; ++n) _Pragma("unroll") for (int k = 0; k < 2; ++k) dst[n][k] = *(const PG8_LAS bf16x8*)(lds + PG8_SB(b, h) + boff + n * 2048 + k * 1024); } while (0)
; #define PG8_MMA(ai, bj, At, Bt) do { __builtin_amdgcn_s_setprio(1); _Pragma("unroll") for (int m = 0; m < 4; ++m) _Pragma("unroll") for (int n = 0; n < 2; ++n) _Pragma("unroll") for (int k = 0; k < 2; ++k) \
;         acc[ai][bj][m][n] = __builtin_amdgcn_mfma_f32_16x16x32_bf16(Bt[n][k], At[m][k], acc[ai][bj][m][n], 0, 0, 0); __builtin_amdgcn_s_setprio(0); } while (0)
; #define PG8_WAIT_V(n) asm volatile("s_waitcnt vmcnt(" #n ")" ::: "memory")
; template <class Epi, class Sched, bool ALIGN_EPI = false, bool SP2 = false>
; __device__ __forceinline__ void gemm_phase(PG8_LAS unsigned char* lds, const Gemm g, const Sched& S, const Epi& E) {
;     ...
;             PG8_LDB(B0, 0, 0); PG8_LDB(B1, 0, 1); PG8_SCHED; PG8_LDA(At, 0, 0); PG8_STAGE(PG8_SA(1, 1), a1 + hstep, voffA);
;             PG8_WAIT_V(8); PG8_WAIT_L(0); PG8_BAR; PG8_MMA(0, 0, At, B0); PG8_MMA(0, 1, At, B1); PG8_BAR; PG8_SCHED;
;             PG8_LDA(At, 0, 1); PG8_STAGE(PG8_SB(0, 0), b2, voffB); PG8_STAGE(PG8_SB(0, 1), b2 + hstep, voffB); PG8_STAGE(PG8_SA(0, 0), a2, voffA);
;             PG8_WAIT_V(8); PG8_WAIT_L(0); PG8_BAR; PG8_MMA(1, 0, At, B0); PG8_MMA(1, 1, At, B1); PG8_BAR; PG8_SCHED;
;             PG8_LDB(B0, 1, 0); PG8_LDB(B1, 1, 1); PG8_SCHED; PG8_LDA(At, 1, 0); PG8_STAGE(PG8_SA(0, 1), a2 + hstep, voffA);
;             PG8_WAIT_V(8); PG8_WAIT_L(0); PG8_BAR; PG8_MMA(0, 0, At, B0); PG8_MMA(0, 1, At, B1); PG8_BAR; PG8_SCHED;
;             PG8_LDA(At, 1, 1); PG8_STAGE(PG8_SB(1, 0), b3, voffB); PG8_STAGE(PG8_SB(1, 1), b3 + hstep, voffB); PG8_STAGE(PG8_SA(1, 0), a3, voffA);
;             PG8_WAIT_V(8); PG8_WAIT_L(0); PG8_BAR; PG8_MMA(1, 0, At, B0); PG8_MMA(1, 1, At, B1); PG8_BAR; PG8_SCHED;
	v_mfma_f32_16x16x32_bf16 v[60:63], v[132:135], v[164:167], v[60:63]
	v_mfma_f32_16x16x32_bf16 v[60:63], v[136:139], v[168:171], v[60:63]
	v_mfma_f32_16x16x32_bf16 v[64:67], v[140:143], v[164:167], v[64:67]
	v_mfma_f32_16x16x32_bf16 v[64:67], v[144:147], v[168:171], v[64:67]
	v_mfma_f32_16x16x32_bf16 v[40:43], v[140:143], v[172:175], v[40:43]
	v_mfma_f32_16x16x32_bf16 v[40:43], v[144:147], v[176:179], v[40:43]
	v_mfma_f32_16x16x32_bf16 v[36:39], v[132:135], v[172:175], v[36:39]
	v_mfma_f32_16x16x32_bf16 v[36:39], v[136:139], v[176:179], v[36:39]
	v_mfma_f32_16x16x32_bf16 v[20:23], v[132:135], v[180:183], v[20:23]
	v_mfma_f32_16x16x32_bf16 v[20:23], v[136:139], v[184:187], v[20:23]
	v_mfma_f32_16x16x32_bf16 v[24:27], v[140:143], v[180:183], v[24:27]
	v_mfma_f32_16x16x32_bf16 v[24:27], v[144:147], v[184:187], v[24:27]
	v_mfma_f32_16x16x32_bf16 v[2:5], v[132:135], v[236:239], v[4:7]
	v_mfma_f32_16x16x32_bf16 v[2:5], v[136:139], v[240:243], v[2:5]
	v_mfma_f32_16x16x32_bf16 v[6:9], v[140:143], v[236:239], v[8:11]
	v_mfma_f32_16x16x32_bf16 v[8:11], v[144:147], v[240:243], v[6:9]
	v_mfma_f32_16x16x32_bf16 v[84:87], v[148:151], v[164:167], v[84:87]
	v_mfma_f32_16x16x32_bf16 v[84:87], v[152:155], v[168:171], v[84:87]
	v_mfma_f32_16x16x32_bf16 v[88:91], v[156:159], v[164:167], v[88:91]
	v_mfma_f32_16x16x32_bf16 v[88:91], v[160:163], v[168:171], v[88:91]
	v_mfma_f32_16x16x32_bf16 v[56:59], v[156:159], v[172:175], v[56:59]
	v_mfma_f32_16x16x32_bf16 v[56:59], v[160:163], v[176:179], v[56:59]
	v_mfma_f32_16x16x32_bf16 v[52:55], v[148:151], v[172:175], v[52:55]
	v_mfma_f32_16x16x32_bf16 v[52:55], v[152:155], v[176:179], v[52:55]
	v_mfma_f32_16x16x32_bf16 v[28:31], v[148:151], v[180:183], v[28:31]
	v_mfma_f32_16x16x32_bf16 v[28:31], v[152:155], v[184:187], v[28:31]
	v_mfma_f32_16x16x32_bf16 v[32:35], v[156:159], v[180:183], v[32:35]
	v_mfma_f32_16x16x32_bf16 v[32:35], v[160:163], v[184:187], v[32:35]
	v_mfma_f32_16x16x32_bf16 v[16:19], v[156:159], v[236:239], v[16:19]
	v_mfma_f32_16x16x32_bf16 v[16:19], v[160:163], v[240:243], v[16:19]
	v_mfma_f32_16x16x32_bf16 v[12:15], v[148:151], v[236:239], v[12:15]
	v_mfma_f32_16x16x32_bf16 v[12:15], v[152:155], v[240:243], v[12:15]
	s_barrier
	s_setprio 0
	s_add_i32 s62, 0, 0x18000
	v_add_u32_e32 v0, s62, v188
	s_add_i32 s63, 0, 0x1c000
	ds_read_b128 v[132:135], v0
	ds_read_b128 v[136:139], v0 offset:1024
	ds_read_b128 v[140:143], v0 offset:2048
	ds_read_b128 v[144:147], v0 offset:3072
	v_add_u32_e32 v0, s63, v188
	ds_read_b128 v[148:151], v0
	ds_read_b128 v[152:155], v0 offset:1024
	ds_read_b128 v[156:159], v0 offset:2048
	ds_read_b128 v[160:163], v0 offset:3072
	s_add_u32 s34, s34, s16
	s_addc_u32 s35, s35, 0
	s_mov_b32 m0, s45
	v_lshl_add_u64 v[6:7], s[34:35], 0, v[190:191]
	ds_read_b128 v[164:167], v235 offset:32768
	ds_read_b128 v[168:171], v235 offset:33792
	ds_read_b128 v[172:175], v235 offset:34816
	ds_read_b128 v[176:179], v235 offset:35840
	ds_read_b128 v[180:183], v235 offset:36864
	ds_read_b128 v[184:187], v235 offset:37888
	ds_read_b128 v[236:239], v235 offset:38912
	ds_read_b128 v[240:243], v235 offset:39936
	global_load_lds_dwordx4 v[6:7], off
	v_lshl_add_u64 v[6:7], s[34:35], 0, v[194:195]
	s_mov_b32 m0, s46
	s_nop 0
	global_load_lds_dwordx4 v[6:7], off
	s_waitcnt vmcnt(8)
	s_waitcnt lgkmcnt(0)
	s_setprio 1
	s_barrier
	v_mfma_f32_16x16x32_bf16 v[116:119], v[132:135], v[164:167], v[116:119]
	v_mfma_f32_16x16x32_bf16 v[116:119], v[136:139], v[168:171], v[116:119]
	v_mfma_f32_16x16x32_bf16 v[120:123], v[140:143], v[164:167], v[120:123]
	v_mfma_f32_16x16x32_bf16 v[120:123], v[144:147], v[168:171], v[120:123]
	v_mfma_f32_16x16x32_bf16 v[104:107], v[140:143], v[172:175], v[104:107]
	v_mfma_f32_16x16x32_bf16 v[104:107], v[144:147], v[176:179], v[104:107]
	v_mfma_f32_16x16x32_bf16 v[100:103], v[132:135], v[172:175], v[100:103]
	v_mfma_f32_16x16x32_bf16 v[100:103], v[136:139], v[176:179], v[100:103]
	v_mfma_f32_16x16x32_bf16 v[76:79], v[132:135], v[180:183], v[76:79]
	v_mfma_f32_16x16x32_bf16 v[76:79], v[136:139], v[184:187], v[76:79]
	v_mfma_f32_16x16x32_bf16 v[80:83], v[140:143], v[180:183], v[80:83]
	v_mfma_f32_16x16x32_bf16 v[80:83], v[144:147], v[184:187], v[80:83]
	v_mfma_f32_16x16x32_bf16 v[48:51], v[140:143], v[236:239], v[48:51]
	v_mfma_f32_16x16x32_bf16 v[48:51], v[144:147], v[240:243], v[48:51]
	v_mfma_f32_16x16x32_bf16 v[44:47], v[132:135], v[236:239], v[44:47]
	v_mfma_f32_16x16x32_bf16 v[44:47], v[136:139], v[240:243], v[44:47]
	v_mfma_f32_16x16x32_bf16 v[124:127], v[148:151], v[164:167], v[124:127]
	v_mfma_f32_16x16x32_bf16 v[124:127], v[152:155], v[168:171], v[124:127]
	v_mfma_f32_16x16x32_bf16 v[128:131], v[156:159], v[164:167], v[128:131]
	v_mfma_f32_16x16x32_bf16 v[128:131], v[160:163], v[168:171], v[128:131]
	v_mfma_f32_16x16x32_bf16 v[112:115], v[156:159], v[172:175], v[112:115]
	v_mfma_f32_16x16x32_bf16 v[112:115], v[160:163], v[176:179], v[112:115]
	v_mfma_f32_16x16x32_bf16 v[108:111], v[148:151], v[172:175], v[108:111]
	v_mfma_f32_16x16x32_bf16 v[108:111], v[152:155], v[176:179], v[108:111]
	v_mfma_f32_16x16x32_bf16 v[92:95], v[148:151], v[180:183], v[92:95]
	v_mfma_f32_16x16x32_bf16 v[92:95], v[152:155], v[184:187], v[92:95]
	v_mfma_f32_16x16x32_bf16 v[96:99], v[156:159], v[180:183], v[96:99]
	v_mfma_f32_16x16x32_bf16 v[96:99], v[160:163], v[184:187], v[96:99]
	v_mfma_f32_16x16x32_bf16 v[72:75], v[156:159], v[236:239], v[72:75]
	v_mfma_f32_16x16x32_bf16 v[72:75], v[160:163], v[240:243], v[72:75]
	v_mfma_f32_16x16x32_bf16 v[68:71], v[148:151], v[236:239], v[68:71]
	v_mfma_f32_16x16x32_bf16 v[68:71], v[152:155], v[240:243], v[68:71]
	s_barrier
; #define PG8_STAGE(bufoff, gbase, voff) do { _Pragma("unroll") for (int _i = 0; _i < 2; ++_i) \
;         __builtin_amdgcn_global_load_lds((const unsigned*)((const char*)(gbase) + (voff)[_i]), (PG8_LAS unsigned*)(lds + (bufoff) + ldsw + _i * 8192), 16, 0, 0); } while (0)
; #define PG8_LDA(dst, b, h) do { _Pragma("unroll") for (int m = 0; m < 4; ++m) _Pragma("unroll") for (int k = 0; k < 2; ++k) dst[m][k] = *(const PG8_LAS bf16x8*)(lds + PG8_SA(b, h) + aoff + m * 2048 + k * 1024); } while (0)
; #define PG8_LDB(dst, b, h) do { _Pragma("unroll") for (int n = 0; n < 2; ++n) _Pragma("unroll") for (int k = 0; k < 2; ++k) dst[n][k] = *(const PG8_LAS bf16x8*)(lds + PG8_SB(b, h) + boff + n * 2048 + k * 1024); } while (0)
; #define PG8_MMA(ai, bj, At, Bt) do { __builtin_amdgcn_s_setprio(1); _Pragma("unroll") for (int m = 0; m < 4; ++m) _Pragma("unroll") for (int n = 0; n < 2; ++n) _Pragma("unroll") for (int k = 0; k < 2; ++k) \
;         acc[ai][bj][m][n] = __builtin_amdgcn_mfma_f32_16x16x32_bf16(Bt[n][k], At[m][k], acc[ai][bj][m][n], 0, 0, 0); __builtin_amdgcn_s_setprio(0); } while (0)
; #define PG8_WAIT_V(n) asm volatile("s_waitcnt vmcnt(" #n ")" ::: "memory")
; #define PG8_WAIT_L(n) asm volatile("s_waitcnt lgkmcnt(" #n ")" ::: "memory")
; #define PG8_BAR __builtin_amdgcn_s_barrier()
; #define PG8_SCHED __builtin_amdgcn_sched_barrier(0)
; template <class Epi, class Sched, bool ALIGN_EPI = false, bool SP2 = false>
; __device__ __forceinline__ void gemm_phase(PG8_LAS unsigned char* lds, const Gemm g, const Sched& S, const Epi& E) {
;     ...
;             PG8_LDB(B0, 1, 0); PG8_LDB(B1, 1, 1); PG8_SCHED; PG8_LDA(At, 1, 0); PG8_STAGE(PG8_SA(0, 1), a2 + hstep, voffA);
;             PG8_WAIT_V(8); PG8_WAIT_L(0); PG8_BAR; PG8_MMA(0, 0, At, B0); PG8_MMA(0, 1, At, B1); PG8_BAR; PG8_SCHED;
;             PG8_LDA(At, 1, 1); PG8_STAGE(PG8_SB(1, 0), b3, voffB); PG8_STAGE(PG8_SB(1, 1), b3 + hstep, voffB); PG8_STAGE(PG8_SA(1, 0), a3, voffA);
;             PG8_WAIT_V(8); PG8_WAIT_L(0); PG8_BAR; PG8_MMA(1, 0, At, B0); PG8_MMA(1, 1, At, B1); PG8_BAR; PG8_SCHED;
	s_setprio 0
	s_add_i32 s34, s62, s41
	v_lshl_add_u64 v[6:7], v[208:209], 0, s[92:93]
	s_mov_b32 m0, s34
	ds_read_b128 v[164:167], v235 offset:49152
	ds_read_b128 v[168:171], v235 offset:50176
	ds_read_b128 v[172:175], v235 offset:51200
	ds_read_b128 v[176:179], v235 offset:52224
	ds_read_b128 v[180:183], v235 offset:53248
	ds_read_b128 v[184:187], v235 offset:54272
	ds_read_b128 v[236:239], v235 offset:55296
	ds_read_b128 v[240:243], v235 offset:56320
	global_load_lds_dwordx4 v[6:7], off
	v_lshl_add_u64 v[6:7], v[244:245], 0, s[92:93]
	s_add_i32 m0, s34, 0x2000
	s_add_i32 s34, s63, s41
	global_load_lds_dwordx4 v[6:7], off
	v_lshl_add_u64 v[6:7], v[246:247], 0, s[92:93]
	s_mov_b32 m0, s34
	s_nop 0
	global_load_lds_dwordx4 v[6:7], off
	v_lshl_add_u64 v[6:7], v[248:249], 0, s[92:93]
	s_add_i32 m0, s34, 0x2000
	s_nop 0
	global_load_lds_dwordx4 v[6:7], off
	v_lshl_add_u64 v[6:7], v[250:251], 0, s[92:93]
	s_mov_b32 m0, s51
	s_nop 0
	global_load_lds_dwordx4 v[6:7], off
	v_lshl_add_u64 v[6:7], v[212:213], 0, s[92:93]
	s_mov_b32 m0, s52
	s_nop 0
	global_load_lds_dwordx4 v[6:7], off
	s_waitcnt vmcnt(8)
	s_waitcnt lgkmcnt(0)
	s_setprio 1
	s_barrier
	v_mfma_f32_16x16x32_bf16 v[60:63], v[132:135], v[164:167], v[60:63]
	v_mfma_f32_16x16x32_bf16 v[60:63], v[136:139], v[168:171], v[60:63]
	v_mfma_f32_16x16x32_bf16 v[64:67], v[140:143], v[164:167], v[64:67]
	v_mfma_f32_16x16x32_bf16 v[64:67], v[144:147], v[168:171], v[64:67]
	v_mfma_f32_16x16x32_bf16 v[40:43], v[140:143], v[172:175], v[40:43]
	v_mfma_f32_16x16x32_bf16 v[40:43], v[144:147], v[176:179], v[40:43]
	v_mfma_f32_16x16x32_bf16 v[36:39], v[132:135], v[172:175], v[36:39]
	v_mfma_f32_16x16x32_bf16 v[36:39], v[136:139], v[176:179], v[36:39]
	v_mfma_f32_16x16x32_bf16 v[20:23], v[132:135], v[180:183], v[20:23]
	v_mfma_f32_16x16x32_bf16 v[20:23], v[136:139], v[184:187], v[20:23]
	v_mfma_f32_16x16x32_bf16 v[24:27], v[140:143], v[180:183], v[24:27]
	v_mfma_f32_16x16x32_bf16 v[24:27], v[144:147], v[184:187], v[24:27]
	v_mfma_f32_16x16x32_bf16 v[8:11], v[140:143], v[236:239], v[8:11]
	v_mfma_f32_16x16x32_bf16 v[8:11], v[144:147], v[240:243], v[8:11]
	v_mfma_f32_16x16x32_bf16 v[2:5], v[132:135], v[236:239], v[2:5]
	v_mfma_f32_16x16x32_bf16 v[4:7], v[136:139], v[240:243], v[2:5]
	v_mfma_f32_16x16x32_bf16 v[84:87], v[148:151], v[164:167], v[84:87]
	v_mfma_f32_16x16x32_bf16 v[84:87], v[152:155], v[168:171], v[84:87]
	v_mfma_f32_16x16x32_bf16 v[88:91], v[156:159], v[164:167], v[88:91]
	v_mfma_f32_16x16x32_bf16 v[88:91], v[160:163], v[168:171], v[88:91]
	v_mfma_f32_16x16x32_bf16 v[56:59], v[156:159], v[172:175], v[56:59]
	v_mfma_f32_16x16x32_bf16 v[56:59], v[160:163], v[176:179], v[56:59]
	v_mfma_f32_16x16x32_bf16 v[52:55], v[148:151], v[172:175], v[52:55]
	v_mfma_f32_16x16x32_bf16 v[52:55], v[152:155], v[176:179], v[52:55]
	v_mfma_f32_16x16x32_bf16 v[28:31], v[148:151], v[180:183], v[28:31]
	v_mfma_f32_16x16x32_bf16 v[28:31], v[152:155], v[184:187], v[28:31]
	v_mfma_f32_16x16x32_bf16 v[32:35], v[156:159], v[180:183], v[32:35]
	v_mfma_f32_16x16x32_bf16 v[32:35], v[160:163], v[184:187], v[32:35]
	v_mfma_f32_16x16x32_bf16 v[16:19], v[156:159], v[236:239], v[16:19]
	v_mfma_f32_16x16x32_bf16 v[16:19], v[160:163], v[240:243], v[16:19]
	v_mfma_f32_16x16x32_bf16 v[12:15], v[148:151], v[236:239], v[12:15]
	v_mfma_f32_16x16x32_bf16 v[12:15], v[152:155], v[240:243], v[12:15]
	s_barrier
	s_setprio 0
	s_add_u32 s30, s30, 0x100
	s_addc_u32 s31, s31, 0
	s_cmp_ge_u32 s2, s47
	s_cbranch_scc1 .LBB0_58
	s_mov_b32 s34, s2
	s_branch .LBB0_54
